# Ph9 tail GEMM K loop software-pipelined: five k-steps of global loads in flight
# baseline (speedup 1.0000x reference)
.LBB0_1306:
	v_add_u32_e32 v0, s8, v120
	v_mad_i64_i32 v[116:117], s[6:7], v0, s16, v[66:67]
	v_add_co_u32_e32 v118, vcc, 0x2c000, v116
	global_load_dwordx4 v[0:3], v[64:65], off
	global_load_dwordx4 v[16:19], v[68:69], off
	global_load_dwordx4 v[4:7], v[116:117], off
	v_addc_co_u32_e32 v119, vcc, 0, v117, vcc
	global_load_dwordx4 v[20:23], v[118:119], off
	global_load_dwordx4 v[136:139], v[64:65], off offset:32
	global_load_dwordx4 v[140:143], v[74:75], off
	global_load_dwordx4 v[144:147], v[116:117], off offset:32
	global_load_dwordx4 v[148:151], v[118:119], off offset:32
	global_load_dwordx4 v[176:179], v[64:65], off offset:64
	global_load_dwordx4 v[180:183], v[76:77], off
	global_load_dwordx4 v[184:187], v[116:117], off offset:64
	global_load_dwordx4 v[188:191], v[118:119], off offset:64
	global_load_dwordx4 v[228:231], v[64:65], off offset:96
	global_load_dwordx4 v[232:235], v[78:79], off
	global_load_dwordx4 v[236:239], v[116:117], off offset:96
	global_load_dwordx4 v[240:243], v[118:119], off offset:96
	global_load_dwordx4 v[244:247], v[64:65], off offset:128
	global_load_dwordx4 v[248:251], v[80:81], off
	global_load_dwordx4 v[220:223], v[116:117], off offset:128
	global_load_dwordx4 v[152:155], v[118:119], off offset:128
	global_load_dwordx4 v[192:195], v[64:65], off offset:160
	global_load_dwordx4 v[196:199], v[82:83], off
	global_load_dwordx4 v[200:203], v[116:117], off offset:160
	global_load_dwordx4 v[156:159], v[118:119], off offset:160
	s_waitcnt vmcnt(20)
	v_mfma_f32_32x32x16_bf16 v[32:47], v[0:3], v[4:7], 0
	v_mfma_f32_32x32x16_bf16 v[48:63], v[0:3], v[20:23], 0
	v_mfma_f32_32x32x16_bf16 v[0:15], v[16:19], v[4:7], 0
	v_mfma_f32_32x32x16_bf16 v[16:31], v[16:19], v[20:23], 0
	s_waitcnt vmcnt(16)
	v_mfma_f32_32x32x16_bf16 v[32:47], v[136:139], v[144:147], v[32:47]
	v_mfma_f32_32x32x16_bf16 v[48:63], v[136:139], v[148:151], v[48:63]
	v_mfma_f32_32x32x16_bf16 v[0:15], v[140:143], v[144:147], v[0:15]
	v_mfma_f32_32x32x16_bf16 v[16:31], v[140:143], v[148:151], v[16:31]
	global_load_dwordx4 v[136:139], v[64:65], off offset:192
	global_load_dwordx4 v[140:143], v[84:85], off
	global_load_dwordx4 v[144:147], v[116:117], off offset:192
	global_load_dwordx4 v[148:151], v[118:119], off offset:192
	s_waitcnt vmcnt(16)
	v_mfma_f32_32x32x16_bf16 v[32:47], v[176:179], v[184:187], v[32:47]
	v_mfma_f32_32x32x16_bf16 v[48:63], v[176:179], v[188:191], v[48:63]
	v_mfma_f32_32x32x16_bf16 v[0:15], v[180:183], v[184:187], v[0:15]
	v_mfma_f32_32x32x16_bf16 v[16:31], v[180:183], v[188:191], v[16:31]
	global_load_dwordx4 v[176:179], v[64:65], off offset:224
	global_load_dwordx4 v[180:183], v[86:87], off
	global_load_dwordx4 v[184:187], v[116:117], off offset:224
	global_load_dwordx4 v[188:191], v[118:119], off offset:224
	s_waitcnt vmcnt(16)
	v_mfma_f32_32x32x16_bf16 v[32:47], v[228:231], v[236:239], v[32:47]
	v_mfma_f32_32x32x16_bf16 v[48:63], v[228:231], v[240:243], v[48:63]
	v_mfma_f32_32x32x16_bf16 v[0:15], v[232:235], v[236:239], v[0:15]
	v_mfma_f32_32x32x16_bf16 v[16:31], v[232:235], v[240:243], v[16:31]
	global_load_dwordx4 v[228:231], v[64:65], off offset:256
	global_load_dwordx4 v[232:235], v[88:89], off
	global_load_dwordx4 v[236:239], v[116:117], off offset:256
	global_load_dwordx4 v[240:243], v[118:119], off offset:256
	s_waitcnt vmcnt(16)
	v_mfma_f32_32x32x16_bf16 v[32:47], v[244:247], v[220:223], v[32:47]
	v_mfma_f32_32x32x16_bf16 v[48:63], v[244:247], v[152:155], v[48:63]
	v_mfma_f32_32x32x16_bf16 v[0:15], v[248:251], v[220:223], v[0:15]
	v_mfma_f32_32x32x16_bf16 v[16:31], v[248:251], v[152:155], v[16:31]
	global_load_dwordx4 v[244:247], v[64:65], off offset:288
	global_load_dwordx4 v[248:251], v[90:91], off
	global_load_dwordx4 v[220:223], v[116:117], off offset:288
	global_load_dwordx4 v[152:155], v[118:119], off offset:288
	s_waitcnt vmcnt(16)
	v_mfma_f32_32x32x16_bf16 v[32:47], v[192:195], v[200:203], v[32:47]
	v_mfma_f32_32x32x16_bf16 v[48:63], v[192:195], v[156:159], v[48:63]
	v_mfma_f32_32x32x16_bf16 v[0:15], v[196:199], v[200:203], v[0:15]
	v_mfma_f32_32x32x16_bf16 v[16:31], v[196:199], v[156:159], v[16:31]
	global_load_dwordx4 v[192:195], v[64:65], off offset:320
	global_load_dwordx4 v[196:199], v[92:93], off
	global_load_dwordx4 v[200:203], v[116:117], off offset:320
	global_load_dwordx4 v[156:159], v[118:119], off offset:320
	s_waitcnt vmcnt(16)
	v_mfma_f32_32x32x16_bf16 v[32:47], v[136:139], v[144:147], v[32:47]
	v_mfma_f32_32x32x16_bf16 v[48:63], v[136:139], v[148:151], v[48:63]
	v_mfma_f32_32x32x16_bf16 v[0:15], v[140:143], v[144:147], v[0:15]
	v_mfma_f32_32x32x16_bf16 v[16:31], v[140:143], v[148:151], v[16:31]
	global_load_dwordx4 v[136:139], v[64:65], off offset:352
	global_load_dwordx4 v[140:143], v[94:95], off
	global_load_dwordx4 v[144:147], v[116:117], off offset:352
	global_load_dwordx4 v[148:151], v[118:119], off offset:352
	s_waitcnt vmcnt(16)
	v_mfma_f32_32x32x16_bf16 v[32:47], v[176:179], v[184:187], v[32:47]
	v_mfma_f32_32x32x16_bf16 v[48:63], v[176:179], v[188:191], v[48:63]
	v_mfma_f32_32x32x16_bf16 v[0:15], v[180:183], v[184:187], v[0:15]
	v_mfma_f32_32x32x16_bf16 v[16:31], v[180:183], v[188:191], v[16:31]
	global_load_dwordx4 v[176:179], v[64:65], off offset:384
	global_load_dwordx4 v[180:183], v[96:97], off
	global_load_dwordx4 v[184:187], v[116:117], off offset:384
	global_load_dwordx4 v[188:191], v[118:119], off offset:384
	s_waitcnt vmcnt(16)
	v_mfma_f32_32x32x16_bf16 v[32:47], v[228:231], v[236:239], v[32:47]
	v_mfma_f32_32x32x16_bf16 v[48:63], v[228:231], v[240:243], v[48:63]
	v_mfma_f32_32x32x16_bf16 v[0:15], v[232:235], v[236:239], v[0:15]
	v_mfma_f32_32x32x16_bf16 v[16:31], v[232:235], v[240:243], v[16:31]
	global_load_dwordx4 v[228:231], v[64:65], off offset:416
	global_load_dwordx4 v[232:235], v[98:99], off
	global_load_dwordx4 v[236:239], v[116:117], off offset:416
	global_load_dwordx4 v[240:243], v[118:119], off offset:416
	s_waitcnt vmcnt(16)
	v_mfma_f32_32x32x16_bf16 v[32:47], v[244:247], v[220:223], v[32:47]
	v_mfma_f32_32x32x16_bf16 v[48:63], v[244:247], v[152:155], v[48:63]
	v_mfma_f32_32x32x16_bf16 v[0:15], v[248:251], v[220:223], v[0:15]
	v_mfma_f32_32x32x16_bf16 v[16:31], v[248:251], v[152:155], v[16:31]
	global_load_dwordx4 v[244:247], v[64:65], off offset:448
	global_load_dwordx4 v[248:251], v[100:101], off
	global_load_dwordx4 v[220:223], v[116:117], off offset:448
	global_load_dwordx4 v[152:155], v[118:119], off offset:448
	s_waitcnt vmcnt(16)
	v_mfma_f32_32x32x16_bf16 v[32:47], v[192:195], v[200:203], v[32:47]
	v_mfma_f32_32x32x16_bf16 v[48:63], v[192:195], v[156:159], v[48:63]
	v_mfma_f32_32x32x16_bf16 v[0:15], v[196:199], v[200:203], v[0:15]
	v_mfma_f32_32x32x16_bf16 v[16:31], v[196:199], v[156:159], v[16:31]
	global_load_dwordx4 v[192:195], v[64:65], off offset:480
	global_load_dwordx4 v[196:199], v[102:103], off
	global_load_dwordx4 v[200:203], v[116:117], off offset:480
	global_load_dwordx4 v[156:159], v[118:119], off offset:480
	s_waitcnt vmcnt(16)
	v_mfma_f32_32x32x16_bf16 v[32:47], v[136:139], v[144:147], v[32:47]
	v_mfma_f32_32x32x16_bf16 v[48:63], v[136:139], v[148:151], v[48:63]
	v_mfma_f32_32x32x16_bf16 v[0:15], v[140:143], v[144:147], v[0:15]
	v_mfma_f32_32x32x16_bf16 v[16:31], v[140:143], v[148:151], v[16:31]
	global_load_dwordx4 v[136:139], v[64:65], off offset:512
	global_load_dwordx4 v[140:143], v[104:105], off
	global_load_dwordx4 v[144:147], v[116:117], off offset:512
	global_load_dwordx4 v[148:151], v[118:119], off offset:512
	s_waitcnt vmcnt(16)
	v_mfma_f32_32x32x16_bf16 v[32:47], v[176:179], v[184:187], v[32:47]
	v_mfma_f32_32x32x16_bf16 v[48:63], v[176:179], v[188:191], v[48:63]
	v_mfma_f32_32x32x16_bf16 v[0:15], v[180:183], v[184:187], v[0:15]
	v_mfma_f32_32x32x16_bf16 v[16:31], v[180:183], v[188:191], v[16:31]
	global_load_dwordx4 v[176:179], v[64:65], off offset:544
	global_load_dwordx4 v[180:183], v[106:107], off
	global_load_dwordx4 v[184:187], v[116:117], off offset:544
	global_load_dwordx4 v[188:191], v[118:119], off offset:544
	s_waitcnt vmcnt(16)
	v_mfma_f32_32x32x16_bf16 v[32:47], v[228:231], v[236:239], v[32:47]
	v_mfma_f32_32x32x16_bf16 v[48:63], v[228:231], v[240:243], v[48:63]
	v_mfma_f32_32x32x16_bf16 v[0:15], v[232:235], v[236:239], v[0:15]
	v_mfma_f32_32x32x16_bf16 v[16:31], v[232:235], v[240:243], v[16:31]
	global_load_dwordx4 v[228:231], v[64:65], off offset:576
	global_load_dwordx4 v[232:235], v[108:109], off
	global_load_dwordx4 v[236:239], v[116:117], off offset:576
	global_load_dwordx4 v[240:243], v[118:119], off offset:576
	s_waitcnt vmcnt(16)
	v_mfma_f32_32x32x16_bf16 v[32:47], v[244:247], v[220:223], v[32:47]
	v_mfma_f32_32x32x16_bf16 v[48:63], v[244:247], v[152:155], v[48:63]
	v_mfma_f32_32x32x16_bf16 v[0:15], v[248:251], v[220:223], v[0:15]
	v_mfma_f32_32x32x16_bf16 v[16:31], v[248:251], v[152:155], v[16:31]
	global_load_dwordx4 v[244:247], v[64:65], off offset:608
	global_load_dwordx4 v[248:251], v[110:111], off
	global_load_dwordx4 v[220:223], v[116:117], off offset:608
	global_load_dwordx4 v[152:155], v[118:119], off offset:608
	s_waitcnt vmcnt(16)
	v_mfma_f32_32x32x16_bf16 v[32:47], v[192:195], v[200:203], v[32:47]
	v_mfma_f32_32x32x16_bf16 v[48:63], v[192:195], v[156:159], v[48:63]
	v_mfma_f32_32x32x16_bf16 v[0:15], v[196:199], v[200:203], v[0:15]
	v_mfma_f32_32x32x16_bf16 v[16:31], v[196:199], v[156:159], v[16:31]
	global_load_dwordx4 v[192:195], v[64:65], off offset:640
	global_load_dwordx4 v[196:199], v[112:113], off
	global_load_dwordx4 v[200:203], v[116:117], off offset:640
	global_load_dwordx4 v[156:159], v[118:119], off offset:640
	s_waitcnt vmcnt(16)
	v_mfma_f32_32x32x16_bf16 v[32:47], v[136:139], v[144:147], v[32:47]
	v_mfma_f32_32x32x16_bf16 v[48:63], v[136:139], v[148:151], v[48:63]
	v_mfma_f32_32x32x16_bf16 v[0:15], v[140:143], v[144:147], v[0:15]
	v_mfma_f32_32x32x16_bf16 v[16:31], v[140:143], v[148:151], v[16:31]
	global_load_dwordx4 v[136:139], v[64:65], off offset:672
	global_load_dwordx4 v[140:143], v[114:115], off
	global_load_dwordx4 v[144:147], v[116:117], off offset:672
	s_nop 0
	global_load_dwordx4 v[116:119], v[118:119], off offset:672
	s_waitcnt vmcnt(16)
	v_mfma_f32_32x32x16_bf16 v[32:47], v[176:179], v[184:187], v[32:47]
	v_mfma_f32_32x32x16_bf16 v[48:63], v[176:179], v[188:191], v[48:63]
	v_mfma_f32_32x32x16_bf16 v[0:15], v[180:183], v[184:187], v[0:15]
	v_mfma_f32_32x32x16_bf16 v[16:31], v[180:183], v[188:191], v[16:31]
	s_waitcnt vmcnt(12)
	v_mfma_f32_32x32x16_bf16 v[32:47], v[228:231], v[236:239], v[32:47]
	v_mfma_f32_32x32x16_bf16 v[48:63], v[228:231], v[240:243], v[48:63]
	v_mfma_f32_32x32x16_bf16 v[0:15], v[232:235], v[236:239], v[0:15]
	v_mfma_f32_32x32x16_bf16 v[16:31], v[232:235], v[240:243], v[16:31]
	s_waitcnt vmcnt(8)
	v_mfma_f32_32x32x16_bf16 v[32:47], v[244:247], v[220:223], v[32:47]
	v_mfma_f32_32x32x16_bf16 v[48:63], v[244:247], v[152:155], v[48:63]
	v_mfma_f32_32x32x16_bf16 v[0:15], v[248:251], v[220:223], v[0:15]
	v_mfma_f32_32x32x16_bf16 v[16:31], v[248:251], v[152:155], v[16:31]
	s_waitcnt vmcnt(4)
	v_mfma_f32_32x32x16_bf16 v[32:47], v[192:195], v[200:203], v[32:47]
	v_mfma_f32_32x32x16_bf16 v[48:63], v[192:195], v[156:159], v[48:63]
	v_mfma_f32_32x32x16_bf16 v[0:15], v[196:199], v[200:203], v[0:15]
	v_mfma_f32_32x32x16_bf16 v[16:31], v[196:199], v[156:159], v[16:31]
	s_waitcnt vmcnt(1)
	v_mfma_f32_32x32x16_bf16 v[32:47], v[136:139], v[144:147], v[32:47]
	s_waitcnt vmcnt(0)
	v_mfma_f32_32x32x16_bf16 v[48:63], v[136:139], v[116:119], v[48:63]
	s_nop 11
	ds_write2_b32 v126, v32, v48 offset1:32
	ds_write2_b32 v126, v33, v49 offset0:64 offset1:96
	ds_write2_b32 v126, v34, v50 offset0:128 offset1:160
	ds_write2_b32 v126, v35, v51 offset0:192 offset1:224
	v_mfma_f32_32x32x16_bf16 v[0:15], v[140:143], v[144:147], v[0:15]
	v_add_u32_e32 v32, 0x800, v126
	ds_write2_b32 v32, v36, v52 offset1:32
	ds_write2_b32 v32, v37, v53 offset0:64 offset1:96
	ds_write2_b32 v32, v38, v54 offset0:128 offset1:160
	ds_write2_b32 v32, v39, v55 offset0:192 offset1:224
	v_add_u32_e32 v32, 0x1000, v126
	ds_write2_b32 v32, v40, v56 offset1:32
	ds_write2_b32 v32, v41, v57 offset0:64 offset1:96
	ds_write2_b32 v32, v42, v58 offset0:128 offset1:160
	ds_write2_b32 v32, v43, v59 offset0:192 offset1:224
	v_add_u32_e32 v32, 0x1800, v126
	ds_write2_b32 v32, v44, v60 offset1:32
	ds_write2_b32 v32, v45, v61 offset0:64 offset1:96
	ds_write2_b32 v32, v46, v62 offset0:128 offset1:160
	ds_write2_b32 v32, v47, v63 offset0:192 offset1:224
	v_add_u32_e32 v32, 0x2000, v126
	v_mfma_f32_32x32x16_bf16 v[16:31], v[140:143], v[116:119], v[16:31]
	s_nop 11
	ds_write2_b32 v32, v0, v16 offset1:32
	ds_write2_b32 v32, v1, v17 offset0:64 offset1:96
	ds_write2_b32 v32, v2, v18 offset0:128 offset1:160
	ds_write2_b32 v32, v3, v19 offset0:192 offset1:224
	v_add_u32_e32 v0, 0x2800, v126
	ds_write2_b32 v0, v4, v20 offset1:32
	ds_write2_b32 v0, v5, v21 offset0:64 offset1:96
	ds_write2_b32 v0, v6, v22 offset0:128 offset1:160
	ds_write2_b32 v0, v7, v23 offset0:192 offset1:224
	v_add_u32_e32 v0, 0x3000, v126
	ds_write2_b32 v0, v8, v24 offset1:32
	ds_write2_b32 v0, v9, v25 offset0:64 offset1:96
	ds_write2_b32 v0, v10, v26 offset0:128 offset1:160
	ds_write2_b32 v0, v11, v27 offset0:192 offset1:224
	v_add_u32_e32 v0, 0x3800, v126
	ds_write2_b32 v0, v12, v28 offset1:32
	ds_write2_b32 v0, v13, v29 offset0:64 offset1:96
	ds_write2_b32 v0, v14, v30 offset0:128 offset1:160
	ds_write2_b32 v0, v15, v31 offset0:192 offset1:224
	s_waitcnt lgkmcnt(0)
	s_barrier
	ds_read_b128 v[0:3], v121
	ds_read_b128 v[4:7], v121 offset:16
	ds_read_b128 v[8:11], v121 offset:16384
	ds_read_b128 v[12:15], v121 offset:16400
	ds_read_b128 v[16:19], v121 offset:32768
	ds_read_b128 v[20:23], v121 offset:32784
	ds_read_b128 v[24:27], v121 offset:49152
	ds_read_b128 v[28:31], v121 offset:49168
	ds_read_b128 v[32:35], v127
	ds_read_b128 v[36:39], v128
	ds_read_b128 v[40:43], v129
	ds_read_b128 v[44:47], v130
	ds_read_b128 v[48:51], v131
	ds_read_b128 v[52:55], v132
	ds_read_b128 v[56:59], v133
	ds_read_b128 v[60:63], v134
	s_waitcnt lgkmcnt(14)
	v_pk_add_f32 v[0:1], v[0:1], 0 op_sel_hi:[1,0]
	v_pk_add_f32 v[4:5], v[4:5], 0 op_sel_hi:[1,0]
	s_waitcnt lgkmcnt(13)
	v_pk_add_f32 v[0:1], v[0:1], v[8:9]
	v_add_u32_e32 v8, s8, v122
	v_ashrrev_i32_e32 v9, 31, v8
	v_pk_add_f32 v[2:3], v[2:3], 0 op_sel_hi:[1,0]
	s_waitcnt lgkmcnt(12)
	v_pk_add_f32 v[4:5], v[4:5], v[12:13]
	v_lshl_add_u64 v[12:13], v[8:9], 1, v[70:71]
	v_pk_add_f32 v[2:3], v[2:3], v[10:11]
	global_load_dwordx4 v[8:11], v[12:13], off
	v_pk_add_f32 v[6:7], v[6:7], 0 op_sel_hi:[1,0]
	s_waitcnt lgkmcnt(11)
	v_pk_add_f32 v[2:3], v[2:3], v[18:19]
	v_pk_add_f32 v[6:7], v[6:7], v[14:15]
	v_pk_add_f32 v[0:1], v[0:1], v[16:17]
	s_waitcnt lgkmcnt(10)
	v_pk_add_f32 v[6:7], v[6:7], v[22:23]
	v_pk_add_f32 v[4:5], v[4:5], v[20:21]
	s_waitcnt lgkmcnt(9)
	v_pk_add_f32 v[2:3], v[2:3], v[26:27]
	v_pk_add_f32 v[0:1], v[0:1], v[24:25]
	s_waitcnt lgkmcnt(8)
	v_pk_add_f32 v[6:7], v[6:7], v[30:31]
	v_pk_add_f32 v[4:5], v[4:5], v[28:29]
	s_waitcnt lgkmcnt(7)
	v_pk_add_f32 v[2:3], v[2:3], v[34:35]
	v_pk_add_f32 v[0:1], v[0:1], v[32:33]
	s_waitcnt lgkmcnt(6)
	v_pk_add_f32 v[6:7], v[6:7], v[38:39]
	v_pk_add_f32 v[4:5], v[4:5], v[36:37]
	s_waitcnt lgkmcnt(5)
	v_pk_add_f32 v[2:3], v[2:3], v[42:43]
	v_pk_add_f32 v[0:1], v[0:1], v[40:41]
	s_waitcnt lgkmcnt(4)
	v_pk_add_f32 v[6:7], v[6:7], v[46:47]
	v_pk_add_f32 v[4:5], v[4:5], v[44:45]
	s_waitcnt lgkmcnt(3)
	v_pk_add_f32 v[2:3], v[2:3], v[50:51]
	v_pk_add_f32 v[0:1], v[0:1], v[48:49]
	s_waitcnt lgkmcnt(2)
	v_pk_add_f32 v[6:7], v[6:7], v[54:55]
	v_pk_add_f32 v[4:5], v[4:5], v[52:53]
	s_waitcnt lgkmcnt(1)
	v_pk_add_f32 v[2:3], v[2:3], v[58:59]
	v_pk_add_f32 v[0:1], v[0:1], v[56:57]
	s_waitcnt lgkmcnt(0)
	v_pk_add_f32 v[6:7], v[6:7], v[62:63]
	v_pk_add_f32 v[4:5], v[4:5], v[60:61]
	s_waitcnt vmcnt(0)
	v_lshlrev_b32_e32 v14, 16, v8
	v_and_b32_e32 v15, 0xffff0000, v8
	v_lshlrev_b32_e32 v8, 16, v9
	v_and_b32_e32 v9, 0xffff0000, v9
	v_lshlrev_b32_e32 v16, 16, v10
	v_and_b32_e32 v17, 0xffff0000, v10
	v_lshlrev_b32_e32 v10, 16, v11
	v_and_b32_e32 v11, 0xffff0000, v11
	v_pk_add_f32 v[8:9], v[2:3], v[8:9]
	v_pk_add_f32 v[14:15], v[0:1], v[14:15]
	v_pk_add_f32 v[6:7], v[6:7], v[10:11]
	v_pk_add_f32 v[4:5], v[4:5], v[16:17]
	v_cvt_pk_bf16_f32 v0, v14, v15
	v_cvt_pk_bf16_f32 v1, v8, v9
	v_cvt_pk_bf16_f32 v2, v4, v5
	v_cvt_pk_bf16_f32 v3, v6, v7
	global_store_dwordx4 v[12:13], v[0:3], off
	s_nop 1
	v_mul_f32_e32 v0, v15, v15
	v_mul_f32_e32 v1, v9, v9
	v_fmac_f32_e32 v0, v14, v14
	v_fmac_f32_e32 v1, v8, v8
	v_add_f32_e32 v0, v0, v1
	v_mul_f32_e32 v1, v5, v5
	v_fmac_f32_e32 v1, v4, v4
	v_add_f32_e32 v0, v1, v0
	v_mul_f32_e32 v1, v7, v7
	v_fmac_f32_e32 v1, v6, v6
	v_add_f32_e32 v0, v1, v0
	ds_bpermute_b32 v1, v123, v0
	s_waitcnt lgkmcnt(0)
	v_add_f32_e32 v0, v0, v1
	ds_bpermute_b32 v1, v124, v0
	s_waitcnt lgkmcnt(0)
	v_add_f32_e32 v0, v0, v1
	ds_bpermute_b32 v1, v125, v0
	s_and_saveexec_b64 s[6:7], s[40:41]
	s_cbranch_execz .LBB0_1305
	s_ashr_i32 s43, s42, 31
	s_waitcnt lgkmcnt(0)
	v_add_f32_e32 v2, v0, v1
	v_lshl_add_u64 v[0:1], s[42:43], 2, v[72:73]
	global_store_dword v[0:1], v2, off
	s_branch .LBB0_1305
